# LN1/LN2 row loops software-pipelined: next row y/y2 loads issued right after unpack, counted vmcnt(4)
# speedup vs baseline: 1.0020x; 1.0020x over previous
.LBB0_977:
	s_andn2_b64 vcc, exec, s[0:1]
	s_cbranch_vccnz .LBB0_1039
	v_readlane_b32 s4, v252, 3
	v_mov_b32_e32 v0, v209
	v_readlane_b32 s5, v252, 4
	v_readlane_b32 s6, v252, 5
	v_readlane_b32 s7, v252, 6
	s_lshl_b32 s0, s2, 3
	v_writelane_b32 v252, s4, 3
	s_add_i32 s0, s0, s81
	s_cmpk_gt_i32 s0, 0x2fff
	v_writelane_b32 v252, s5, 4
	v_writelane_b32 v252, s6, 5
	v_writelane_b32 v252, s7, 6
	s_cbranch_scc1 .LBB0_989
	v_readlane_b32 s4, v253, 63
	v_readlane_b32 s5, v254, 0
	s_mov_b32 s9, s5
	s_mul_i32 s8, s65, 0x9000
	s_lshl_b64 s[4:5], s[8:9], 2
	s_add_u32 s12, s78, s4
	s_addc_u32 s13, s79, s5
	s_lshl_b32 s8, s65, 11
	v_readlane_b32 s56, v252, 7
	v_readlane_b32 s6, v254, 1
	s_lshl_b64 s[4:5], s[8:9], 2
	v_readlane_b32 s62, v252, 13
	v_lshlrev_b32_e32 v2, 3, v0
	v_readlane_b32 s7, v254, 2
	s_mov_b32 s1, s9
	v_readlane_b32 s63, v252, 14
	s_add_u32 s6, s62, s4
	v_ashrrev_i32_e32 v3, 31, v2
	v_writelane_b32 v253, s0, 63
	v_readlane_b32 s60, v252, 11
	s_addc_u32 s7, s63, s5
	v_writelane_b32 v254, s1, 0
	v_lshlrev_b64 v[102:103], 1, v[2:3]
	v_lshlrev_b64 v[106:107], 2, v[2:3]
	v_add_u32_e32 v4, 0x204, v2
	v_add_u32_e32 v6, 0x404, v2
	v_add_u32_e32 v2, 0x604, v2
	v_writelane_b32 v254, s2, 1
	v_readlane_b32 s61, v252, 12
	s_add_u32 s4, s60, s4
	v_ashrrev_i32_e32 v7, 31, v6
	v_ashrrev_i32_e32 v3, 31, v2
	v_writelane_b32 v254, s3, 2
	s_addc_u32 s5, s61, s5
	v_lshlrev_b64 v[116:117], 2, v[6:7]
	v_lshlrev_b64 v[126:127], 2, v[2:3]
	s_ashr_i32 s1, s0, 31
	v_lshl_add_u64 v[108:109], s[4:5], 0, v[106:107]
	v_lshl_add_u64 v[110:111], s[6:7], 0, v[106:107]
	v_lshl_add_u64 v[118:119], s[4:5], 0, v[116:117]
	v_lshl_add_u64 v[120:121], s[6:7], 0, v[116:117]
	v_lshl_add_u64 v[128:129], s[4:5], 0, v[126:127]
	v_lshl_add_u64 v[130:131], s[6:7], 0, v[126:127]
	s_lshl_b32 s4, s72, 3
	s_lshl_b64 s[6:7], s[0:1], 3
	v_readlane_b32 s8, v254, 27
	s_add_u32 s5, s78, s6
	v_readlane_b32 s9, v254, 28
	s_addc_u32 s7, s79, s7
	s_add_u32 s6, s5, 0x300000
	v_lshl_add_u64 v[104:105], s[8:9], 0, v[102:103]
	s_mov_b64 s[8:9], 0x1000
	v_lshl_add_u64 v[112:113], v[108:109], 0, s[8:9]
	v_lshl_add_u64 v[114:115], v[110:111], 0, s[8:9]
	s_mov_b64 s[8:9], 0x1800
	s_addc_u32 s7, s7, 0
	s_ashr_i32 s5, s4, 31
	v_lshl_add_u64 v[122:123], v[108:109], 0, s[8:9]
	v_lshl_add_u64 v[124:125], v[110:111], 0, s[8:9]
	s_lshl_b64 s[8:9], s[4:5], 3
	s_lshl_b64 s[18:19], s[0:1], 12
	s_add_u32 s10, s78, s18
	s_addc_u32 s11, s79, s19
	s_lshl_b64 s[16:17], s[4:5], 12
	v_readlane_b32 s64, v252, 15
	v_readlane_b32 s65, v252, 16
	v_readlane_b32 s67, v252, 18
	v_readlane_b32 s68, v252, 19
	v_readlane_b32 s69, v252, 20
	v_readlane_b32 s70, v252, 21
	v_readlane_b32 s71, v252, 22
	v_readlane_b32 s60, v254, 15
	v_ashrrev_i32_e32 v5, 31, v4
	s_add_u32 s18, s92, s18
	s_mov_b64 s[68:69], 0x8000
	s_mov_b64 s[70:71], 0x27400000
	v_readlane_b32 s65, v254, 18
	s_movk_i32 s64, 0x1800
	s_movk_i32 s67, 0x800
	s_mov_b64 s[62:63], 0x60
	v_readlane_b32 s61, v254, 16
	v_cmp_eq_u32_e64 s[36:37], 0, v0
	s_addc_u32 s19, s93, s19
	s_mov_b32 s1, -1
	v_lshlrev_b64 v[132:133], 2, v[4:5]
	v_readlane_b32 s57, v252, 8
	v_readlane_b32 s58, v252, 9
	v_readlane_b32 s59, v252, 10
	v_readlane_b32 s66, v252, 17
	s_add_u32 s24, s18, 0x1e400000
	s_addc_u32 s25, s19, 0
	v_lshl_add_u64 v[242:243], s[24:25], 0, v[102:103]
	global_load_dwordx4 v[226:229], v[242:243], off
	global_load_dwordx4 v[230:233], v[242:243], off offset:1024
	global_load_dwordx4 v[234:237], v[242:243], off offset:2048
	global_load_dwordx4 v[238:241], v[242:243], off offset:3072
	s_branch .LBB0_981

.LBB0_981:
	v_lshl_add_u64 v[134:135], s[18:19], 0, v[102:103]
	s_cmpk_gt_i32 s0, 0x1fff
	s_cselect_b64 s[20:21], -1, 0

.LBB0_985:
	s_waitcnt vmcnt(4)
	v_lshlrev_b32_e32 v144, 16, v226
	v_and_b32_e32 v145, 0xffff0000, v226
	v_lshlrev_b32_e32 v146, 16, v227
	v_and_b32_e32 v147, 0xffff0000, v227
	v_lshlrev_b32_e32 v136, 16, v228
	v_and_b32_e32 v137, 0xffff0000, v228
	v_lshlrev_b32_e32 v140, 16, v229
	v_and_b32_e32 v141, 0xffff0000, v229
	v_lshlrev_b32_e32 v138, 16, v230
	v_and_b32_e32 v139, 0xffff0000, v230
	v_lshlrev_b32_e32 v142, 16, v231
	v_and_b32_e32 v143, 0xffff0000, v231
	v_lshlrev_b32_e32 v86, 16, v232
	v_and_b32_e32 v87, 0xffff0000, v232
	v_lshlrev_b32_e32 v98, 16, v233
	v_and_b32_e32 v99, 0xffff0000, v233
	v_lshlrev_b32_e32 v88, 16, v234
	v_and_b32_e32 v89, 0xffff0000, v234
	v_lshlrev_b32_e32 v100, 16, v235
	v_and_b32_e32 v101, 0xffff0000, v235
	v_lshlrev_b32_e32 v78, 16, v236
	v_and_b32_e32 v79, 0xffff0000, v236
	v_lshlrev_b32_e32 v82, 16, v237
	v_and_b32_e32 v83, 0xffff0000, v237
	v_lshlrev_b32_e32 v80, 16, v238
	v_and_b32_e32 v81, 0xffff0000, v238
	v_lshlrev_b32_e32 v84, 16, v239
	v_and_b32_e32 v85, 0xffff0000, v239
	v_lshlrev_b32_e32 v74, 16, v240
	v_and_b32_e32 v75, 0xffff0000, v240
	v_lshlrev_b32_e32 v76, 16, v241
	s_andn2_b64 vcc, exec, s[20:21]
	v_and_b32_e32 v77, 0xffff0000, v241
	s_cbranch_vccnz .LBB0_987
	v_lshlrev_b32_e32 v148, 16, v174
	v_and_b32_e32 v149, 0xffff0000, v174
	v_lshlrev_b32_e32 v156, 16, v175
	v_and_b32_e32 v157, 0xffff0000, v175
	v_pk_add_f32 v[156:157], v[146:147], v[156:157]
	v_pk_add_f32 v[144:145], v[144:145], v[148:149]
	v_lshlrev_b32_e32 v146, 16, v176
	v_and_b32_e32 v147, 0xffff0000, v176
	v_lshlrev_b32_e32 v148, 16, v177
	v_and_b32_e32 v149, 0xffff0000, v177
	s_mov_b64 s[20:21], 0x1e400000
	v_pk_add_f32 v[140:141], v[140:141], v[148:149]
	v_pk_add_f32 v[136:137], v[136:137], v[146:147]
	v_lshl_add_u64 v[150:151], v[134:135], 0, s[20:21]
	v_cvt_pk_bf16_f32 v146, v144, v145
	v_cvt_pk_bf16_f32 v147, v156, v157
	v_cvt_pk_bf16_f32 v148, v136, v137
	v_cvt_pk_bf16_f32 v149, v140, v141
	global_store_dwordx4 v[150:151], v[146:149], off
	v_lshlrev_b32_e32 v136, 16, v148
	v_and_b32_e32 v137, 0xffff0000, v148
	v_lshlrev_b32_e32 v140, 16, v149
	v_and_b32_e32 v141, 0xffff0000, v149
	v_lshlrev_b32_e32 v148, 16, v178
	v_and_b32_e32 v149, 0xffff0000, v178
	v_lshlrev_b32_e32 v150, 16, v179
	v_and_b32_e32 v151, 0xffff0000, v179
	v_pk_add_f32 v[142:143], v[142:143], v[150:151]
	v_pk_add_f32 v[138:139], v[138:139], v[148:149]
	v_lshlrev_b32_e32 v148, 16, v180
	v_and_b32_e32 v149, 0xffff0000, v180
	v_lshlrev_b32_e32 v150, 16, v181
	v_and_b32_e32 v151, 0xffff0000, v181
	s_mov_b64 s[20:21], 0x1e400400
	v_pk_add_f32 v[98:99], v[98:99], v[150:151]
	v_pk_add_f32 v[86:87], v[86:87], v[148:149]
	v_lshl_add_u64 v[152:153], v[134:135], 0, s[20:21]
	v_cvt_pk_bf16_f32 v148, v138, v139
	v_cvt_pk_bf16_f32 v149, v142, v143
	v_cvt_pk_bf16_f32 v150, v86, v87
	v_cvt_pk_bf16_f32 v151, v98, v99
	global_store_dwordx4 v[152:153], v[148:151], off
	v_lshlrev_b32_e32 v138, 16, v148
	v_and_b32_e32 v139, 0xffff0000, v148
	v_lshlrev_b32_e32 v142, 16, v149
	v_and_b32_e32 v143, 0xffff0000, v149
	v_lshlrev_b32_e32 v86, 16, v150
	v_and_b32_e32 v87, 0xffff0000, v150
	v_lshlrev_b32_e32 v98, 16, v151
	v_and_b32_e32 v99, 0xffff0000, v151
	v_lshlrev_b32_e32 v148, 16, v182
	v_and_b32_e32 v149, 0xffff0000, v182
	v_lshlrev_b32_e32 v150, 16, v183
	v_and_b32_e32 v151, 0xffff0000, v183
	v_pk_add_f32 v[100:101], v[100:101], v[150:151]
	v_pk_add_f32 v[88:89], v[88:89], v[148:149]
	v_lshlrev_b32_e32 v148, 16, v184
	v_and_b32_e32 v149, 0xffff0000, v184
	v_lshlrev_b32_e32 v150, 16, v185
	v_and_b32_e32 v151, 0xffff0000, v185
	s_mov_b64 s[20:21], 0x1e400800
	v_pk_add_f32 v[82:83], v[82:83], v[150:151]
	v_pk_add_f32 v[78:79], v[78:79], v[148:149]
	v_lshl_add_u64 v[154:155], v[134:135], 0, s[20:21]
	v_cvt_pk_bf16_f32 v148, v88, v89
	v_cvt_pk_bf16_f32 v149, v100, v101
	v_cvt_pk_bf16_f32 v150, v78, v79
	v_cvt_pk_bf16_f32 v151, v82, v83
	global_store_dwordx4 v[154:155], v[148:151], off
	v_lshlrev_b32_e32 v88, 16, v148
	v_and_b32_e32 v89, 0xffff0000, v148
	v_lshlrev_b32_e32 v100, 16, v149
	v_and_b32_e32 v101, 0xffff0000, v149
	v_lshlrev_b32_e32 v78, 16, v150
	v_and_b32_e32 v79, 0xffff0000, v150
	v_lshlrev_b32_e32 v82, 16, v151
	v_and_b32_e32 v83, 0xffff0000, v151
	v_lshlrev_b32_e32 v148, 16, v186
	v_and_b32_e32 v149, 0xffff0000, v186
	v_lshlrev_b32_e32 v150, 16, v187
	v_and_b32_e32 v151, 0xffff0000, v187
	v_pk_add_f32 v[84:85], v[84:85], v[150:151]
	v_pk_add_f32 v[80:81], v[80:81], v[148:149]
	v_lshlrev_b32_e32 v148, 16, v188
	v_and_b32_e32 v149, 0xffff0000, v188
	v_lshlrev_b32_e32 v150, 16, v189
	v_and_b32_e32 v151, 0xffff0000, v189
	s_mov_b64 s[20:21], 0x1e400c00
	v_pk_add_f32 v[150:151], v[76:77], v[150:151]
	v_pk_add_f32 v[76:77], v[74:75], v[148:149]
	v_lshl_add_u64 v[134:135], v[134:135], 0, s[20:21]
	v_cvt_pk_bf16_f32 v74, v80, v81
	v_cvt_pk_bf16_f32 v75, v84, v85
	v_cvt_pk_bf16_f32 v76, v76, v77
	v_cvt_pk_bf16_f32 v77, v150, v151
	v_lshlrev_b32_e32 v144, 16, v146
	v_and_b32_e32 v145, 0xffff0000, v146
	v_lshlrev_b32_e32 v146, 16, v147
	v_and_b32_e32 v147, 0xffff0000, v147
	global_store_dwordx4 v[134:135], v[74:77], off
	v_lshlrev_b32_e32 v80, 16, v74
	v_and_b32_e32 v81, 0xffff0000, v74
	v_lshlrev_b32_e32 v84, 16, v75
	v_and_b32_e32 v85, 0xffff0000, v75
	v_lshlrev_b32_e32 v74, 16, v76
	v_and_b32_e32 v75, 0xffff0000, v76
	v_lshlrev_b32_e32 v76, 16, v77
	v_and_b32_e32 v77, 0xffff0000, v77
.LBB0_987:
	s_add_i32 s22, s0, s4
	s_cmpk_lt_i32 s22, 0x3000
	s_cbranch_scc0 .Lln1_nopf
	s_add_u32 s24, s18, s16
	s_addc_u32 s25, s19, s17
	s_add_u32 s24, s24, 0x1e400000
	s_addc_u32 s25, s25, 0
	v_lshl_add_u64 v[242:243], s[24:25], 0, v[102:103]
	global_load_dwordx4 v[226:229], v[242:243], off
	global_load_dwordx4 v[230:233], v[242:243], off offset:1024
	global_load_dwordx4 v[234:237], v[242:243], off offset:2048
	global_load_dwordx4 v[238:241], v[242:243], off offset:3072
	s_cmpk_lt_i32 s22, 0x2000
	s_cbranch_scc1 .Lln1_nopf
	s_add_i32 s24, s22, 0xffffe000
	s_mov_b32 s25, 0
	s_lshl_b64 s[24:25], s[24:25], 12
	v_lshl_add_u64 v[242:243], v[104:105], 0, s[24:25]
	global_load_dwordx4 v[174:177], v[242:243], off
	global_load_dwordx4 v[178:181], v[242:243], off offset:1024
	global_load_dwordx4 v[182:185], v[242:243], off offset:2048
	global_load_dwordx4 v[186:189], v[242:243], off offset:3072

.LBB0_1395:
	v_readlane_b32 s4, v252, 3
	v_mov_b32_e32 v0, v209
	v_readlane_b32 s5, v252, 4
	v_readlane_b32 s6, v252, 5
	v_readlane_b32 s7, v252, 6
	s_lshl_b32 s0, s2, 3
	v_writelane_b32 v252, s4, 3
	s_add_i32 s0, s0, s81
	s_cmpk_gt_i32 s0, 0x2fff
	v_writelane_b32 v252, s5, 4
	v_writelane_b32 v252, s6, 5
	v_writelane_b32 v252, s7, 6
	s_cbranch_scc1 .LBB0_1424
	s_cmp_lg_u32 s65, 3
	v_readlane_b32 s8, v252, 3
	s_cselect_b64 s[4:5], -1, 0
	s_cmp_eq_u32 s65, 3
	v_readlane_b32 s9, v252, 4
	v_readlane_b32 s10, v252, 5
	v_readlane_b32 s11, v252, 6
	s_cselect_b32 s23, s9, 0
	s_cselect_b32 s22, s8, 0
	v_readlane_b32 s8, v253, 63
	v_readlane_b32 s9, v254, 0
	s_mul_i32 s8, s65, 0x9000
	s_lshl_b64 s[6:7], s[8:9], 2
	s_add_u32 s1, s78, s6
	s_addc_u32 s6, s79, s7
	s_add_u32 s12, s1, 0x124000
	s_addc_u32 s13, s6, 0
	s_lshl_b32 s8, s65, 11
	v_readlane_b32 s56, v252, 7
	s_lshl_b64 s[6:7], s[8:9], 2
	v_readlane_b32 s66, v252, 17
	v_lshlrev_b32_e32 v2, 3, v0
	v_readlane_b32 s67, v252, 18
	s_add_u32 s8, s66, s6
	v_add_u32_e32 v10, 0x404, v2
	v_readlane_b32 s10, v254, 1
	s_mov_b32 s1, s9
	v_readlane_b32 s64, v252, 15
	s_addc_u32 s9, s67, s7
	v_ashrrev_i32_e32 v3, 31, v2
	v_ashrrev_i32_e32 v11, 31, v10
	v_readlane_b32 s11, v254, 2
	v_readlane_b32 s65, v252, 16
	s_add_u32 s10, s64, s6
	v_lshlrev_b64 v[4:5], 1, v[2:3]
	v_lshlrev_b64 v[104:105], 2, v[2:3]
	v_add_u32_e32 v6, 0x200, v2
	v_add_u32_e32 v110, 0x204, v2
	v_add_u32_e32 v8, 0x400, v2
	v_lshlrev_b64 v[116:117], 2, v[10:11]
	v_add_u32_e32 v10, 0x600, v2
	v_add_u32_e32 v2, 0x604, v2
	s_addc_u32 s11, s65, s7
	v_ashrrev_i32_e32 v3, 31, v2
	v_writelane_b32 v253, s0, 63
	s_cmp_lg_u64 s[22:23], 0
	v_lshlrev_b64 v[126:127], 2, v[2:3]
	v_writelane_b32 v254, s1, 0
	v_writelane_b32 v254, s2, 1
	s_cselect_b64 s[6:7], -1, 0
	v_lshl_add_u64 v[106:107], s[10:11], 0, v[104:105]
	v_lshl_add_u64 v[118:119], s[10:11], 0, v[116:117]
	v_lshl_add_u64 v[128:129], s[10:11], 0, v[126:127]
	s_add_u32 s10, s78, 0x18400000
	v_writelane_b32 v254, s3, 2
	v_ashrrev_i32_e32 v7, 31, v6
	v_ashrrev_i32_e32 v9, 31, v8
	v_ashrrev_i32_e32 v11, 31, v10
	s_addc_u32 s11, s79, 0
	s_ashr_i32 s1, s0, 31
	v_lshl_add_u64 v[108:109], s[8:9], 0, v[104:105]
	v_lshl_add_u64 v[120:121], s[8:9], 0, v[116:117]
	v_lshl_add_u64 v[130:131], s[8:9], 0, v[126:127]
	v_lshl_add_u64 v[132:133], s[10:11], 0, v[4:5]
	s_lshl_b32 s8, s72, 3
	v_lshl_add_u64 v[134:135], v[6:7], 1, s[10:11]
	v_lshl_add_u64 v[136:137], v[8:9], 1, s[10:11]
	v_lshl_add_u64 v[138:139], v[10:11], 1, s[10:11]
	s_lshl_b64 s[10:11], s[0:1], 3
	s_add_u32 s9, s78, s10
	s_addc_u32 s11, s79, s11
	v_readlane_b32 s14, v254, 27
	s_add_u32 s10, s9, 0x300000
	v_readlane_b32 s15, v254, 28
	s_addc_u32 s11, s11, 0
	s_ashr_i32 s9, s8, 31
	v_readlane_b32 s60, v252, 11
	v_readlane_b32 s61, v252, 12
	v_lshl_add_u64 v[102:103], s[14:15], 0, v[4:5]
	s_mov_b64 s[14:15], 0x1000
	s_lshl_b64 s[16:17], s[8:9], 3
	s_lshl_b64 s[18:19], s[0:1], 12
	s_lshl_b64 s[20:21], s[8:9], 12
	s_lshl_b64 s[24:25], s[0:1], 13
	v_readlane_b32 s62, v252, 13
	v_readlane_b32 s63, v252, 14
	v_readlane_b32 s68, v252, 19
	v_readlane_b32 s69, v252, 20
	v_readlane_b32 s70, v252, 21
	v_readlane_b32 s71, v252, 22
	v_readlane_b32 s60, v254, 15
	v_lshl_add_u64 v[112:113], v[106:107], 0, s[14:15]
	v_lshl_add_u64 v[114:115], v[108:109], 0, s[14:15]
	s_mov_b64 s[14:15], 0x1800
	s_add_u32 s22, s22, s24
	v_lshlrev_b64 v[142:143], 2, v[8:9]
	s_mov_b64 s[68:69], 0x8000
	s_mov_b64 s[70:71], 0x27400000
	s_mov_b64 s[62:63], 0x60
	v_readlane_b32 s61, v254, 16
	s_movk_i32 s67, 0x800
	s_movk_i32 s64, 0x1800
	v_readlane_b32 s65, v254, 18
	v_ashrrev_i32_e32 v111, 31, v110
	v_lshl_add_u64 v[122:123], v[106:107], 0, s[14:15]
	v_lshl_add_u64 v[124:125], v[108:109], 0, s[14:15]
	v_cmp_eq_u32_e64 s[36:37], 0, v0
	v_lshl_add_u64 v[140:141], s[92:93], 0, v[4:5]
	s_addc_u32 s23, s23, s25
	s_lshl_b64 s[24:25], s[8:9], 13
	v_or_b32_e32 v142, 16, v142
	v_lshlrev_b64 v[144:145], 2, v[10:11]
	s_mov_b32 s1, -1
	v_readlane_b32 s57, v252, 8
	v_readlane_b32 s58, v252, 9
	v_readlane_b32 s59, v252, 10
	s_add_u32 s42, s18, 0x31000000
	s_addc_u32 s43, s19, 0
	v_lshl_add_u64 v[242:243], v[140:141], 0, s[42:43]
	global_load_dwordx4 v[226:229], v[242:243], off
	global_load_dwordx4 v[230:233], v[242:243], off offset:1024
	global_load_dwordx4 v[234:237], v[242:243], off offset:2048
	global_load_dwordx4 v[238:241], v[242:243], off offset:3072
	s_branch .LBB0_1398

.LBB0_1398:
	v_lshl_add_u64 v[146:147], v[140:141], 0, s[18:19]
	s_cmpk_gt_i32 s0, 0x1fff
	s_cselect_b64 s[38:39], -1, 0

.LBB0_1404:
	s_waitcnt vmcnt(4)
	v_lshlrev_b32_e32 v158, 16, v226
	v_and_b32_e32 v159, 0xffff0000, v226
	v_lshlrev_b32_e32 v160, 16, v227
	v_and_b32_e32 v161, 0xffff0000, v227
	v_lshlrev_b32_e32 v150, 16, v228
	v_and_b32_e32 v151, 0xffff0000, v228
	v_lshlrev_b32_e32 v154, 16, v229
	v_and_b32_e32 v155, 0xffff0000, v229
	v_lshlrev_b32_e32 v152, 16, v230
	v_and_b32_e32 v153, 0xffff0000, v230
	v_lshlrev_b32_e32 v156, 16, v231
	v_and_b32_e32 v157, 0xffff0000, v231
	v_lshlrev_b32_e32 v96, 16, v232
	v_and_b32_e32 v97, 0xffff0000, v232
	v_lshlrev_b32_e32 v100, 16, v233
	v_and_b32_e32 v101, 0xffff0000, v233
	v_lshlrev_b32_e32 v98, 16, v234
	v_and_b32_e32 v99, 0xffff0000, v234
	v_lshlrev_b32_e32 v148, 16, v235
	v_and_b32_e32 v149, 0xffff0000, v235
	v_lshlrev_b32_e32 v86, 16, v236
	v_and_b32_e32 v87, 0xffff0000, v236
	v_lshlrev_b32_e32 v92, 16, v237
	v_and_b32_e32 v93, 0xffff0000, v237
	v_lshlrev_b32_e32 v88, 16, v238
	v_and_b32_e32 v89, 0xffff0000, v238
	v_lshlrev_b32_e32 v94, 16, v239
	v_and_b32_e32 v95, 0xffff0000, v239
	v_lshlrev_b32_e32 v90, 16, v240
	v_and_b32_e32 v91, 0xffff0000, v240
	v_lshlrev_b32_e32 v82, 16, v241
	s_andn2_b64 vcc, exec, s[38:39]
	v_and_b32_e32 v83, 0xffff0000, v241
	s_cbranch_vccnz .LBB0_1406
	v_lshlrev_b32_e32 v162, 16, v190
	v_and_b32_e32 v163, 0xffff0000, v190
	v_lshlrev_b32_e32 v164, 16, v191
	v_and_b32_e32 v165, 0xffff0000, v191
	v_pk_add_f32 v[164:165], v[160:161], v[164:165]
	v_pk_add_f32 v[158:159], v[158:159], v[162:163]
	v_lshlrev_b32_e32 v160, 16, v192
	v_and_b32_e32 v161, 0xffff0000, v192
	v_lshlrev_b32_e32 v162, 16, v193
	v_and_b32_e32 v163, 0xffff0000, v193
	s_mov_b64 s[38:39], 0x31000000
	v_pk_add_f32 v[154:155], v[154:155], v[162:163]
	v_pk_add_f32 v[150:151], v[150:151], v[160:161]
	v_lshl_add_u64 v[84:85], v[146:147], 0, s[38:39]
	v_cvt_pk_bf16_f32 v160, v158, v159
	v_cvt_pk_bf16_f32 v161, v164, v165
	v_cvt_pk_bf16_f32 v162, v150, v151
	v_cvt_pk_bf16_f32 v163, v154, v155
	global_store_dwordx4 v[84:85], v[160:163], off
	v_lshlrev_b32_e32 v150, 16, v162
	v_and_b32_e32 v151, 0xffff0000, v162
	v_lshlrev_b32_e32 v154, 16, v163
	v_and_b32_e32 v155, 0xffff0000, v163
	v_lshlrev_b32_e32 v84, 16, v194
	v_and_b32_e32 v85, 0xffff0000, v194
	v_lshlrev_b32_e32 v162, 16, v195
	v_and_b32_e32 v163, 0xffff0000, v195
	v_pk_add_f32 v[156:157], v[156:157], v[162:163]
	v_pk_add_f32 v[84:85], v[152:153], v[84:85]
	v_lshlrev_b32_e32 v152, 16, v196
	v_and_b32_e32 v153, 0xffff0000, v196
	v_lshlrev_b32_e32 v162, 16, v197
	v_and_b32_e32 v163, 0xffff0000, v197
	s_mov_b64 s[38:39], 0x31000400
	v_pk_add_f32 v[100:101], v[100:101], v[162:163]
	v_pk_add_f32 v[96:97], v[96:97], v[152:153]
	v_lshl_add_u64 v[170:171], v[146:147], 0, s[38:39]
	v_cvt_pk_bf16_f32 v162, v84, v85
	v_cvt_pk_bf16_f32 v163, v156, v157
	v_cvt_pk_bf16_f32 v164, v96, v97
	v_cvt_pk_bf16_f32 v165, v100, v101
	global_store_dwordx4 v[170:171], v[162:165], off
	v_lshlrev_b32_e32 v152, 16, v162
	v_and_b32_e32 v153, 0xffff0000, v162
	v_lshlrev_b32_e32 v156, 16, v163
	v_and_b32_e32 v157, 0xffff0000, v163
	v_lshlrev_b32_e32 v84, 16, v198
	v_and_b32_e32 v85, 0xffff0000, v198
	v_lshlrev_b32_e32 v162, 16, v199
	v_and_b32_e32 v163, 0xffff0000, v199
	v_pk_add_f32 v[148:149], v[148:149], v[162:163]
	v_pk_add_f32 v[84:85], v[98:99], v[84:85]
	v_lshlrev_b32_e32 v98, 16, v200
	v_and_b32_e32 v99, 0xffff0000, v200
	v_lshlrev_b32_e32 v162, 16, v201
	v_and_b32_e32 v163, 0xffff0000, v201
	s_mov_b64 s[38:39], 0x31000800
	v_pk_add_f32 v[92:93], v[92:93], v[162:163]
	v_pk_add_f32 v[86:87], v[86:87], v[98:99]
	v_lshl_add_u64 v[172:173], v[146:147], 0, s[38:39]
	v_lshlrev_b32_e32 v96, 16, v164
	v_and_b32_e32 v97, 0xffff0000, v164
	v_lshlrev_b32_e32 v100, 16, v165
	v_and_b32_e32 v101, 0xffff0000, v165
	v_cvt_pk_bf16_f32 v162, v84, v85
	v_cvt_pk_bf16_f32 v163, v148, v149
	v_cvt_pk_bf16_f32 v164, v86, v87
	v_cvt_pk_bf16_f32 v165, v92, v93
	global_store_dwordx4 v[172:173], v[162:165], off
	v_lshlrev_b32_e32 v98, 16, v162
	v_and_b32_e32 v99, 0xffff0000, v162
	v_lshlrev_b32_e32 v148, 16, v163
	v_and_b32_e32 v149, 0xffff0000, v163
	v_lshlrev_b32_e32 v84, 16, v202
	v_and_b32_e32 v85, 0xffff0000, v202
	v_lshlrev_b32_e32 v162, 16, v203
	v_and_b32_e32 v163, 0xffff0000, v203
	v_pk_add_f32 v[94:95], v[94:95], v[162:163]
	v_pk_add_f32 v[84:85], v[88:89], v[84:85]
	v_lshlrev_b32_e32 v88, 16, v204
	v_and_b32_e32 v89, 0xffff0000, v204
	v_lshlrev_b32_e32 v162, 16, v205
	v_and_b32_e32 v163, 0xffff0000, v205
	s_mov_b64 s[38:39], 0x31000c00
	v_pk_add_f32 v[162:163], v[82:83], v[162:163]
	v_pk_add_f32 v[88:89], v[90:91], v[88:89]
	v_lshl_add_u64 v[146:147], v[146:147], 0, s[38:39]
	v_cvt_pk_bf16_f32 v82, v84, v85
	v_cvt_pk_bf16_f32 v83, v94, v95
	v_cvt_pk_bf16_f32 v84, v88, v89
	v_cvt_pk_bf16_f32 v85, v162, v163
	v_lshlrev_b32_e32 v158, 16, v160
	v_and_b32_e32 v159, 0xffff0000, v160
	v_lshlrev_b32_e32 v160, 16, v161
	v_and_b32_e32 v161, 0xffff0000, v161
	v_lshlrev_b32_e32 v86, 16, v164
	v_and_b32_e32 v87, 0xffff0000, v164
	v_lshlrev_b32_e32 v92, 16, v165
	v_and_b32_e32 v93, 0xffff0000, v165
	global_store_dwordx4 v[146:147], v[82:85], off
	v_lshlrev_b32_e32 v88, 16, v82
	v_and_b32_e32 v89, 0xffff0000, v82
	v_lshlrev_b32_e32 v94, 16, v83
	v_and_b32_e32 v95, 0xffff0000, v83
	v_lshlrev_b32_e32 v90, 16, v84
	v_and_b32_e32 v91, 0xffff0000, v84
	v_lshlrev_b32_e32 v82, 16, v85
	v_and_b32_e32 v83, 0xffff0000, v85
.LBB0_1406:
	s_add_i32 s40, s0, s8
	s_cmpk_lt_i32 s40, 0x3000
	s_cbranch_scc0 .Lln2_nopf
	v_lshl_add_u64 v[242:243], v[140:141], 0, s[20:21]
	s_add_u32 s42, s18, 0x31000000
	s_addc_u32 s43, s19, 0
	v_lshl_add_u64 v[242:243], v[242:243], 0, s[42:43]
	global_load_dwordx4 v[226:229], v[242:243], off
	global_load_dwordx4 v[230:233], v[242:243], off offset:1024
	global_load_dwordx4 v[234:237], v[242:243], off offset:2048
	global_load_dwordx4 v[238:241], v[242:243], off offset:3072
	s_cmpk_lt_i32 s40, 0x2000
	s_cbranch_scc1 .Lln2_nopf
	s_add_i32 s40, s40, 0xffffe000
	s_mov_b32 s41, 0
	s_lshl_b64 s[40:41], s[40:41], 12
	v_lshl_add_u64 v[242:243], v[102:103], 0, s[40:41]
	global_load_dwordx4 v[190:193], v[242:243], off
	global_load_dwordx4 v[194:197], v[242:243], off offset:1024
	global_load_dwordx4 v[198:201], v[242:243], off offset:2048
	global_load_dwordx4 v[202:205], v[242:243], off offset:3072
